# LN1: each lane handles 2 x 8 consecutive channels: 2 dwordx4 loads + 2 dwordx4 stores per row instead of 4+4 dwordx2 (VMEM instructions per row halved)
# speedup vs baseline: 1.0038x; 1.0038x over previous
.LBB0_297:
	s_or_b64 exec, exec, s[6:7]
	s_waitcnt lgkmcnt(0)
	s_barrier
	s_load_dwordx2 s[8:9], s[0:1], 0xd8
	v_mov_b32_e32 v34, v194
	s_mov_b32 s3, 0x10200
	v_ashrrev_i32_e32 v0, 6, v34
	v_add_u32_e32 v32, s33, v0
	v_cmp_gt_i32_e32 vcc, s3, v32
	v_mbcnt_lo_u32_b32 v182, -1, 0
	s_and_saveexec_b64 s[10:11], vcc
	s_cbranch_execz .LBB0_300
	s_load_dwordx4 s[12:15], s[0:1], 0x30
	v_lshlrev_b32_e32 v0, 5, v34
	v_and_b32_e32 v33, 0x7e0, v0
	s_mov_b64 s[6:7], 0x37a00000
	s_ashr_i32 s31, s30, 31
	s_waitcnt lgkmcnt(0)
	global_load_dwordx4 v[0:3], v33, s[12:13]
	global_load_dwordx4 v[4:7], v33, s[14:15]
	global_load_dwordx4 v[8:11], v33, s[12:13] offset:16
	global_load_dwordx4 v[12:15], v33, s[14:15] offset:16
	global_load_dwordx4 v[16:19], v33, s[12:13] offset:2048
	global_load_dwordx4 v[20:23], v33, s[14:15] offset:2048
	global_load_dwordx4 v[24:27], v33, s[12:13] offset:2064
	global_load_dwordx4 v[28:31], v33, s[14:15] offset:2064
	v_mbcnt_hi_u32_b32 v33, -1, v182
	v_and_b32_e32 v35, 64, v33
	v_add_u32_e32 v35, 64, v35
	v_xor_b32_e32 v36, 1, v33
	v_cmp_lt_i32_e32 vcc, v36, v35
	v_xor_b32_e32 v37, 2, v33
	v_xor_b32_e32 v38, 4, v33
	v_cndmask_b32_e32 v36, v33, v36, vcc
	v_cmp_lt_i32_e32 vcc, v37, v35
	v_xor_b32_e32 v39, 8, v33
	v_xor_b32_e32 v40, 16, v33
	v_cndmask_b32_e32 v37, v33, v37, vcc
	v_cmp_lt_i32_e32 vcc, v38, v35
	v_xor_b32_e32 v41, 32, v33
	v_lshlrev_b32_e32 v36, 2, v36
	v_cndmask_b32_e32 v38, v33, v38, vcc
	v_cmp_lt_i32_e32 vcc, v39, v35
	v_lshlrev_b32_e32 v37, 2, v37
	v_lshlrev_b32_e32 v38, 2, v38
	v_cndmask_b32_e32 v39, v33, v39, vcc
	v_cmp_lt_i32_e32 vcc, v40, v35
	v_lshlrev_b32_e32 v39, 2, v39
	s_lshl_b64 s[12:13], s[30:31], 11
	v_cndmask_b32_e32 v40, v33, v40, vcc
	v_cmp_lt_i32_e32 vcc, v41, v35
	v_lshlrev_b32_e32 v40, 2, v40
	s_mov_b64 s[14:15], 0
	v_cndmask_b32_e32 v33, v33, v41, vcc
	v_lshlrev_b32_e32 v41, 2, v33
	v_ashrrev_i32_e32 v33, 31, v32
	v_lshlrev_b64 v[42:43], 11, v[32:33]
	v_and_b32_e32 v33, 63, v34
	v_lshl_or_b32 v42, v33, 4, v42
	v_lshl_add_u64 v[34:35], s[8:9], 0, v[42:43]
	v_lshl_add_u64 v[34:35], v[34:35], 0, s[6:7]
	v_mov_b32_e32 v33, 0x3727c5ac
	s_mov_b32 s3, 0xf800000
	v_mov_b32_e32 v42, 0x260
	s_mov_b32 s16, 0xd6f00000
	s_mov_b32 s17, 0xd6f01000
	s_mov_b32 s18, 0x101ff
.LBB0_299:
	global_load_dwordx4 v[44:47], v[34:35], off
	global_load_dwordx4 v[48:51], v[34:35], off offset:1024
	v_add_co_u32_e32 v52, vcc, s16, v34
	v_add_u32_e32 v32, s30, v32
	s_nop 0
	v_addc_co_u32_e32 v53, vcc, -1, v35, vcc
	v_add_co_u32_e32 v54, vcc, s17, v34
	s_waitcnt vmcnt(1)
	v_lshlrev_b32_e32 v57, 16, v45
	v_lshlrev_b32_e32 v56, 16, v44
	v_and_b32_e32 v45, 0xffff0000, v45
	v_and_b32_e32 v44, 0xffff0000, v44
	v_lshlrev_b32_e32 v59, 16, v47
	v_lshlrev_b32_e32 v58, 16, v46
	v_and_b32_e32 v47, 0xffff0000, v47
	v_and_b32_e32 v46, 0xffff0000, v46
	v_pk_add_f32 v[68:69], v[56:57], v[44:45]
	v_pk_add_f32 v[70:71], v[58:59], v[46:47]
	s_waitcnt vmcnt(0)
	v_lshlrev_b32_e32 v60, 16, v48
	v_and_b32_e32 v61, 0xffff0000, v48
	v_lshlrev_b32_e32 v48, 16, v49
	v_and_b32_e32 v49, 0xffff0000, v49
	s_waitcnt vmcnt(0)
	v_and_b32_e32 v65, 0xffff0000, v50
	v_add_f32_e32 v43, v68, v69
	v_pk_add_f32 v[68:69], v[70:71], v[70:71] op_sel:[0,1] op_sel_hi:[1,0]
	v_lshlrev_b32_e32 v63, 16, v50
	v_lshlrev_b32_e32 v67, 16, v51
	v_and_b32_e32 v51, 0xffff0000, v51
	v_add_f32_e32 v66, v60, v61
	v_add_f32_e32 v50, v48, v49
	v_add_f32_e32 v62, 0, v43
	v_mov_b32_e32 v69, v65
	v_pk_add_f32 v[70:71], v[66:67], v[50:51]
	v_pk_add_f32 v[68:69], v[62:63], v[68:69]
	v_addc_co_u32_e32 v55, vcc, -1, v35, vcc
	v_pk_add_f32 v[68:69], v[68:69], v[70:71]
	v_cmp_lt_i32_e32 vcc, s18, v32
	v_add_f32_e32 v43, v68, v69
	ds_bpermute_b32 v50, v36, v43
	s_or_b64 s[14:15], vcc, s[14:15]
	v_lshl_add_u64 v[34:35], v[34:35], 0, s[12:13]
	s_waitcnt lgkmcnt(0)
	v_add_f32_e32 v43, v43, v50
	ds_bpermute_b32 v50, v37, v43
	s_waitcnt lgkmcnt(0)
	v_add_f32_e32 v43, v43, v50
	ds_bpermute_b32 v50, v38, v43
	s_waitcnt lgkmcnt(0)
	v_add_f32_e32 v43, v43, v50
	ds_bpermute_b32 v50, v39, v43
	s_waitcnt lgkmcnt(0)
	v_add_f32_e32 v43, v43, v50
	ds_bpermute_b32 v50, v40, v43
	s_waitcnt lgkmcnt(0)
	v_add_f32_e32 v43, v43, v50
	ds_bpermute_b32 v50, v41, v43
	s_waitcnt lgkmcnt(0)
	v_add_f32_e32 v43, v43, v50
	v_fmac_f32_e32 v44, 0xba800000, v43
	v_fmac_f32_e32 v45, 0xba800000, v43
	v_fmac_f32_e32 v57, 0xba800000, v43
	v_fmac_f32_e32 v46, 0xba800000, v43
	v_fmac_f32_e32 v47, 0xba800000, v43
	v_fmac_f32_e32 v59, 0xba800000, v43
	v_fmac_f32_e32 v56, 0xba800000, v43
	v_fmac_f32_e32 v58, 0xba800000, v43
	v_fmac_f32_e32 v60, 0xba800000, v43
	v_mov_b32_e32 v68, v57
	v_mov_b32_e32 v69, v45
	v_mov_b32_e32 v57, v44
	v_mov_b32_e32 v44, v59
	v_mov_b32_e32 v45, v47
	v_mov_b32_e32 v59, v46
	v_fmac_f32_e32 v61, 0xba800000, v43
	v_fmac_f32_e32 v48, 0xba800000, v43
	v_mul_f32_e32 v46, v60, v60
	v_pk_mul_f32 v[70:71], v[68:69], v[68:69]
	v_pk_mul_f32 v[72:73], v[56:57], v[56:57]
	v_pk_mul_f32 v[74:75], v[44:45], v[44:45]
	v_pk_mul_f32 v[76:77], v[58:59], v[58:59]
	v_fmac_f32_e32 v49, 0xba800000, v43
	v_fmac_f32_e32 v63, 0xba800000, v43
	v_mul_f32_e32 v62, v48, v48
	v_pk_fma_f32 v[46:47], v[60:61], v[60:61], v[46:47] op_sel_hi:[1,1,0]
	v_pk_mov_b32 v[80:81], v[72:73], v[70:71] op_sel:[1,0]
	v_mov_b32_e32 v73, v71
	v_pk_mov_b32 v[70:71], v[76:77], v[74:75] op_sel:[1,0]
	v_mov_b32_e32 v77, v75
	v_mov_b32_e32 v64, v63
	v_pk_fma_f32 v[78:79], v[48:49], v[48:49], v[62:63] op_sel_hi:[1,1,0]
	v_mul_f32_e32 v46, v63, v63
	v_pk_add_f32 v[62:63], v[80:81], v[72:73]
	v_pk_add_f32 v[70:71], v[70:71], v[76:77]
	v_fmac_f32_e32 v51, 0xba800000, v43
	v_fmac_f32_e32 v67, 0xba800000, v43
	v_fmac_f32_e32 v65, 0xba800000, v43
	v_pk_add_f32 v[62:63], v[62:63], v[62:63] op_sel_hi:[0,1]
	v_pk_add_f32 v[70:71], v[70:71], v[70:71] op_sel_hi:[0,1]
	v_mul_f32_e32 v78, v65, v65
	v_mul_f32_e32 v62, v67, v67
	v_mul_f32_e32 v70, v51, v51
	v_pk_add_f32 v[46:47], v[46:47], v[78:79]
	v_pk_add_f32 v[62:63], v[62:63], v[70:71]
	v_mov_b32_e32 v50, v67
	v_pk_add_f32 v[46:47], v[46:47], v[62:63]
	s_nop 0
	v_add_f32_e32 v43, v46, v47
	ds_bpermute_b32 v46, v36, v43
	s_waitcnt lgkmcnt(0)
	v_add_f32_e32 v43, v43, v46
	ds_bpermute_b32 v46, v37, v43
	s_waitcnt lgkmcnt(0)
	v_add_f32_e32 v43, v43, v46
	ds_bpermute_b32 v46, v38, v43
	s_waitcnt lgkmcnt(0)
	v_add_f32_e32 v43, v43, v46
	ds_bpermute_b32 v46, v39, v43
	s_waitcnt lgkmcnt(0)
	v_add_f32_e32 v43, v43, v46
	ds_bpermute_b32 v46, v40, v43
	s_waitcnt lgkmcnt(0)
	v_add_f32_e32 v43, v43, v46
	ds_bpermute_b32 v46, v41, v43
	s_waitcnt lgkmcnt(0)
	v_add_f32_e32 v43, v43, v46
	v_fmamk_f32 v43, v43, 0x3a800000, v33
	v_mul_f32_e32 v46, 0x4f800000, v43
	v_cmp_gt_f32_e32 vcc, s3, v43
	s_nop 1
	v_cndmask_b32_e32 v43, v43, v46, vcc
	v_sqrt_f32_e32 v46, v43
	s_nop 0
	v_add_u32_e32 v47, -1, v46
	v_add_u32_e32 v62, 1, v46
	v_fma_f32 v63, -v47, v46, v43
	v_fma_f32 v66, -v62, v46, v43
	v_cmp_ge_f32_e64 s[6:7], 0, v63
	s_nop 1
	v_cndmask_b32_e64 v46, v46, v47, s[6:7]
	v_cmp_lt_f32_e64 s[6:7], 0, v66
	s_nop 1
	v_cndmask_b32_e64 v46, v46, v62, s[6:7]
	v_mul_f32_e32 v47, 0x37800000, v46
	v_cndmask_b32_e32 v46, v46, v47, vcc
	v_cmp_class_f32_e32 vcc, v43, v42
	s_nop 1
	v_cndmask_b32_e32 v43, v46, v43, vcc
	v_div_scale_f32 v46, s[6:7], v43, v43, 1.0
	v_rcp_f32_e32 v62, v46
	v_div_scale_f32 v47, vcc, 1.0, v43, 1.0
	v_fma_f32 v63, -v46, v62, 1.0
	v_fmac_f32_e32 v62, v63, v62
	v_mul_f32_e32 v63, v47, v62
	v_fma_f32 v66, -v46, v63, v47
	v_fmac_f32_e32 v63, v66, v62
	v_fma_f32 v46, -v46, v63, v47
	v_div_fmas_f32 v46, v46, v62, v63
	v_div_fixup_f32 v46, v46, v43, 1.0
	v_pk_mul_f32 v[56:57], v[56:57], v[46:47] op_sel_hi:[1,0]
	v_pk_mul_f32 v[62:63], v[68:69], v[46:47] op_sel_hi:[1,0]
	v_pk_mul_f32 v[58:59], v[58:59], v[46:47] op_sel_hi:[1,0]
	v_pk_mul_f32 v[44:45], v[44:45], v[46:47] op_sel_hi:[1,0]
	v_pk_mul_f32 v[60:61], v[60:61], v[46:47] op_sel_hi:[1,0]
	v_pk_mul_f32 v[48:49], v[48:49], v[46:47] op_sel_hi:[1,0]
	v_pk_mul_f32 v[64:65], v[64:65], v[46:47] op_sel_hi:[1,0]
	v_pk_mul_f32 v[46:47], v[50:51], v[46:47] op_sel_hi:[1,0]
	v_pk_fma_f32 v[50:51], v[2:3], v[62:63], v[6:7]
	v_pk_fma_f32 v[56:57], v[0:1], v[56:57], v[4:5]
	v_pk_fma_f32 v[44:45], v[10:11], v[44:45], v[14:15]
	v_pk_fma_f32 v[58:59], v[8:9], v[58:59], v[12:13]
	v_pk_fma_f32 v[48:49], v[18:19], v[48:49], v[22:23]
	v_pk_fma_f32 v[60:61], v[16:17], v[60:61], v[20:21]
	v_pk_fma_f32 v[46:47], v[26:27], v[46:47], v[30:31]
	v_pk_fma_f32 v[62:63], v[24:25], v[64:65], v[28:29]
	v_cvt_pk_bf16_f32 v56, v56, v57
	v_cvt_pk_bf16_f32 v57, v50, v51
	v_cvt_pk_bf16_f32 v58, v58, v59
	v_cvt_pk_bf16_f32 v59, v44, v45
	v_cvt_pk_bf16_f32 v44, v60, v61
	v_cvt_pk_bf16_f32 v45, v48, v49
	v_cvt_pk_bf16_f32 v47, v46, v47
	v_cvt_pk_bf16_f32 v46, v62, v63
	global_store_dwordx4 v[52:53], v[56:59], off
	global_store_dwordx4 v[54:55], v[44:47], off offset:-3072
	s_andn2_b64 exec, exec, s[14:15]
	s_cbranch_execnz .LBB0_299
